# rotK with the bias-table LDS reads issued after the 6th PV MFMA
# baseline (speedup 1.0000x reference)
; template <int MODE>
; __device__ __forceinline__ void step64(St& S, const bf16x8 (&qf)[4], int t, int qpos0, bool diag, bool first, float cq, float cfar, const LAS float* tab,
;                                        const LAS unsigned char* buf, unsigned vaddr, int r32, int hi) {
;     ...
;         if (qpos0 - (t * 64 + 31) >= 128) {
;             const float c = cfar - S.m;
; #pragma unroll
;             for (int r = 0; r < 16; ++r) sa[r] = c;
;         } else {
;             const int dd = qpos0 + r32 - t * 64 + 128;
; #pragma unroll
;             for (int r = 0; r < 16; ++r) { int idx = dd - crow(r, hi); idx = idx < 0 ? 0 : (idx > 256 ? 256 : idx); sa[r] = tab[idx] - S.m; }
;     ...
;     for (int r = 0; r < 16; ++r) { sa[r] = __builtin_amdgcn_exp2f(sa[r]); sb[r] = __builtin_amdgcn_exp2f(sb[r]); }
;     asm volatile("s_waitcnt lgkmcnt(0)" ::: "memory");
;     __builtin_amdgcn_sched_barrier(0);
;     u32x4 pa0, pa1, pb0, pb1;
;     pa0.x = pk2(sa[0], sa[1]); pa0.y = pk2(sa[2], sa[3]); pa0.z = pk2(sa[4], sa[5]); pa0.w = pk2(sa[6], sa[7]);
;     pa1.x = pk2(sa[8], sa[9]); pa1.y = pk2(sa[10], sa[11]); pa1.z = pk2(sa[12], sa[13]); pa1.w = pk2(sa[14], sa[15]);
;     pb0.x = pk2(sb[0], sb[1]); pb0.y = pk2(sb[2], sb[3]); pb0.z = pk2(sb[4], sb[5]); pb0.w = pk2(sb[6], sb[7]);
;     pb1.x = pk2(sb[8], sb[9]); pb1.y = pk2(sb[10], sb[11]); pb1.z = pk2(sb[12], sb[13]); pb1.w = pk2(sb[14], sb[15]);
;     ...
;     S.o0 = __builtin_amdgcn_mfma_f32_32x32x16_bf16(ATT_VF(0), ATT_PF(pa0), S.o0, 0, 0, 0);
;     S.o1 = __builtin_amdgcn_mfma_f32_32x32x16_bf16(ATT_VF(2), ATT_PF(pa0), S.o1, 0, 0, 0);
;     S.o0 = __builtin_amdgcn_mfma_f32_32x32x16_bf16(ATT_VF(1), ATT_PF(pa1), S.o0, 0, 0, 0);
;     S.o1 = __builtin_amdgcn_mfma_f32_32x32x16_bf16(ATT_VF(3), ATT_PF(pa1), S.o1, 0, 0, 0);
;     S.o0 = __builtin_amdgcn_mfma_f32_32x32x16_bf16(ATT_VF(4), ATT_PF(pb0), S.o0, 0, 0, 0);
;     S.o1 = __builtin_amdgcn_mfma_f32_32x32x16_bf16(ATT_VF(6), ATT_PF(pb0), S.o1, 0, 0, 0);
;     S.o0 = __builtin_amdgcn_mfma_f32_32x32x16_bf16(ATT_VF(5), ATT_PF(pb1), S.o0, 0, 0, 0);
;     S.o1 = __builtin_amdgcn_mfma_f32_32x32x16_bf16(ATT_VF(7), ATT_PF(pb1), S.o1, 0, 0, 0);
;     ...
;     float l0 = 0.f, l1 = 0.f, l2 = 0.f, l3 = 0.f;
; #pragma unroll
;     for (int r = 0; r < 16; r += 2) { l0 += sa[r]; l1 += sa[r + 1]; l2 += sb[r]; l3 += sb[r + 1]; }
;     S.l += (l0 + l1) + (l2 + l3);
.Lk0_nodma:
	s_cmp_le_i32 s44, s34
	s_cbranch_scc1 .Lk0_noY
	s_add_i32 s35, s41, 1
	s_cmp_gt_i32 s44, s35
	s_cbranch_scc1 .Lk0_noY
	v_exp_f32_e32 v48, v48
	v_exp_f32_e32 v49, v49
	v_exp_f32_e32 v50, v50
	v_exp_f32_e32 v51, v51
	v_exp_f32_e32 v52, v52
	v_exp_f32_e32 v53, v53
	v_exp_f32_e32 v54, v54
	v_exp_f32_e32 v55, v55
	v_cvt_pk_bf16_f32 v218, v48, v49
	v_cvt_pk_bf16_f32 v219, v50, v51
	v_cvt_pk_bf16_f32 v220, v52, v53
	v_cvt_pk_bf16_f32 v221, v54, v55
	v_exp_f32_e32 v56, v56
	v_exp_f32_e32 v57, v57
	v_mfma_f32_32x32x16_bf16 v[32:47], v[112:115], v[218:221], v[32:47]
	v_exp_f32_e32 v58, v58
	v_exp_f32_e32 v59, v59
	v_exp_f32_e32 v60, v60
	v_exp_f32_e32 v61, v61
	v_exp_f32_e32 v62, v62
	v_exp_f32_e32 v63, v63
	v_mfma_f32_32x32x16_bf16 v[16:31], v[108:111], v[218:221], v[16:31]
	v_cvt_pk_bf16_f32 v222, v56, v57
	v_cvt_pk_bf16_f32 v223, v58, v59
	v_cvt_pk_bf16_f32 v224, v60, v61
	v_cvt_pk_bf16_f32 v225, v62, v63
	v_add_f32_e32 v0, v48, v50
	v_add_f32_e32 v0, v0, v52
	v_add_f32_e32 v14, v49, v51
	v_add_f32_e32 v14, v14, v53
	v_mfma_f32_32x32x16_bf16 v[32:47], v[104:107], v[222:225], v[32:47]
	v_exp_f32_e32 v64, v64
	v_exp_f32_e32 v65, v65
	v_exp_f32_e32 v66, v66
	v_exp_f32_e32 v67, v67
	v_exp_f32_e32 v68, v68
	v_exp_f32_e32 v69, v69
	v_exp_f32_e32 v70, v70
	v_exp_f32_e32 v71, v71
	v_mfma_f32_32x32x16_bf16 v[16:31], v[100:103], v[222:225], v[16:31]
	v_cvt_pk_bf16_f32 v226, v64, v65
	v_cvt_pk_bf16_f32 v227, v66, v67
	v_cvt_pk_bf16_f32 v228, v68, v69
	v_cvt_pk_bf16_f32 v229, v70, v71
	v_add_f32_e32 v0, v0, v54
	v_add_f32_e32 v0, v0, v56
	v_add_f32_e32 v14, v14, v55
	v_add_f32_e32 v14, v14, v57
	v_mfma_f32_32x32x16_bf16 v[32:47], v[96:99], v[226:229], v[32:47]
	v_exp_f32_e32 v72, v72
	v_exp_f32_e32 v73, v73
	v_exp_f32_e32 v74, v74
	v_exp_f32_e32 v75, v75
	v_exp_f32_e32 v76, v76
	v_exp_f32_e32 v77, v77
	v_exp_f32_e32 v78, v78
	v_exp_f32_e32 v79, v79
	v_mfma_f32_32x32x16_bf16 v[16:31], v[10:13], v[226:229], v[16:31]
	s_cmp_gt_i32 s44, s41
	s_cbranch_scc1 .Lk0a_notab
	s_add_i32 s35, s48, 63
	s_min_i32 s35, s35, 192
	s_lshl_b32 s35, s35, 2
	v_subrev_u32_e32 v235, s35, v238
	s_waitcnt lgkmcnt(0)
	ds_read_b128 v[158:161], v235
	ds_read_b128 v[162:165], v235 offset:32
	ds_read_b128 v[166:169], v235 offset:64
	ds_read_b128 v[170:173], v235 offset:96
	ds_read_b128 v[174:177], v235 offset:128
	ds_read_b128 v[180:183], v235 offset:160
	ds_read_b128 v[116:119], v235 offset:192
	ds_read_b64 v[236:237], v235 offset:224
	ds_read_b32 v178, v235 offset:232
	ds_read_b32 v185, v235 offset:236
.Lk0a_notab:
	v_cvt_pk_bf16_f32 v230, v72, v73
	v_cvt_pk_bf16_f32 v231, v74, v75
	v_cvt_pk_bf16_f32 v232, v76, v77
	v_cvt_pk_bf16_f32 v233, v78, v79
	v_add_f32_e32 v0, v0, v58
	v_add_f32_e32 v0, v0, v60
	v_add_f32_e32 v0, v0, v62
	v_add_f32_e32 v14, v14, v59
	v_add_f32_e32 v14, v14, v61
	v_add_f32_e32 v14, v14, v63
	v_mfma_f32_32x32x16_bf16 v[32:47], v[6:9], v[230:233], v[32:47]
	v_add_f32_e32 v15, v64, v66
	v_add_f32_e32 v15, v15, v68
	v_add_f32_e32 v15, v15, v70
	v_add_f32_e32 v15, v15, v72
	v_add_f32_e32 v234, v65, v67
	v_add_f32_e32 v234, v234, v69
	v_add_f32_e32 v234, v234, v71
	v_add_f32_e32 v234, v234, v73
	v_mfma_f32_32x32x16_bf16 v[16:31], v[2:5], v[230:233], v[16:31]
	v_add_f32_e32 v15, v15, v74
	v_add_f32_e32 v15, v15, v76
	v_add_f32_e32 v15, v15, v78
	v_add_f32_e32 v234, v234, v75
	v_add_f32_e32 v234, v234, v77
	v_add_f32_e32 v234, v234, v79
	v_add_f32_e32 v0, v0, v14
	v_add_f32_e32 v15, v15, v234
	v_add_f32_e32 v0, v0, v15
	v_add_f32_e32 v150, v150, v0
	s_cmp_gt_i32 s44, s41
	s_cbranch_scc1 .Lk0a_end
	s_waitcnt lgkmcnt(0)
	v_sub_f32_e32 v48, v158, v157
	v_sub_f32_e32 v49, v159, v157
	v_sub_f32_e32 v50, v160, v157
	v_sub_f32_e32 v51, v161, v157
	v_sub_f32_e32 v52, v162, v157
	v_sub_f32_e32 v53, v163, v157
	v_sub_f32_e32 v54, v164, v157
	v_sub_f32_e32 v55, v165, v157
	v_sub_f32_e32 v56, v166, v157
	v_sub_f32_e32 v57, v167, v157
	v_sub_f32_e32 v58, v168, v157
	v_sub_f32_e32 v59, v169, v157
	v_sub_f32_e32 v60, v170, v157
	v_sub_f32_e32 v61, v171, v157
	v_sub_f32_e32 v62, v172, v157
	v_sub_f32_e32 v63, v173, v157
	v_sub_f32_e32 v64, v174, v157
	v_sub_f32_e32 v65, v175, v157
	v_sub_f32_e32 v66, v176, v157
	v_sub_f32_e32 v67, v177, v157
	v_sub_f32_e32 v68, v180, v157
	v_sub_f32_e32 v69, v181, v157
	v_sub_f32_e32 v70, v182, v157
	v_sub_f32_e32 v71, v183, v157
	v_sub_f32_e32 v72, v116, v157
	v_sub_f32_e32 v73, v117, v157
	v_sub_f32_e32 v74, v118, v157
	v_sub_f32_e32 v75, v119, v157
	v_sub_f32_e32 v76, v236, v157
	v_sub_f32_e32 v77, v237, v157
	v_sub_f32_e32 v78, v178, v157
	v_sub_f32_e32 v79, v185, v157

; __device__ __forceinline__ unsigned pk2(float lo, float hi) { f32x2_t v = {lo, hi}; bf16x2_t b = __builtin_convertvector(v, bf16x2_t); return __builtin_bit_cast(unsigned, b); }
; template <int MODE>
; __device__ __forceinline__ void step64(St& S, const bf16x8 (&qf)[4], int t, int qpos0, bool diag, bool first, float cq, float cfar, const LAS float* tab,
;                                        const LAS unsigned char* buf, unsigned vaddr, int r32, int hi) {
;     ...
;     for (int r = 0; r < 16; ++r) { sa[r] = __builtin_amdgcn_exp2f(sa[r]); sb[r] = __builtin_amdgcn_exp2f(sb[r]); }
;     asm volatile("s_waitcnt lgkmcnt(0)" ::: "memory");
;     __builtin_amdgcn_sched_barrier(0);
;     u32x4 pa0, pa1, pb0, pb1;
;     pa0.x = pk2(sa[0], sa[1]); pa0.y = pk2(sa[2], sa[3]); pa0.z = pk2(sa[4], sa[5]); pa0.w = pk2(sa[6], sa[7]);
;     pa1.x = pk2(sa[8], sa[9]); pa1.y = pk2(sa[10], sa[11]); pa1.z = pk2(sa[12], sa[13]); pa1.w = pk2(sa[14], sa[15]);
;     pb0.x = pk2(sb[0], sb[1]); pb0.y = pk2(sb[2], sb[3]); pb0.z = pk2(sb[4], sb[5]); pb0.w = pk2(sb[6], sb[7]);
;     pb1.x = pk2(sb[8], sb[9]); pb1.y = pk2(sb[10], sb[11]); pb1.z = pk2(sb[12], sb[13]); pb1.w = pk2(sb[14], sb[15]);
;     ...
;     S.o0 = __builtin_amdgcn_mfma_f32_32x32x16_bf16(ATT_VF(0), ATT_PF(pa0), S.o0, 0, 0, 0);
;     S.o1 = __builtin_amdgcn_mfma_f32_32x32x16_bf16(ATT_VF(2), ATT_PF(pa0), S.o1, 0, 0, 0);
;     S.o0 = __builtin_amdgcn_mfma_f32_32x32x16_bf16(ATT_VF(1), ATT_PF(pa1), S.o0, 0, 0, 0);
;     S.o1 = __builtin_amdgcn_mfma_f32_32x32x16_bf16(ATT_VF(3), ATT_PF(pa1), S.o1, 0, 0, 0);
.Lk0_epi:
	s_add_i32 s35, s41, 1
	s_cmp_gt_i32 s44, s35
	s_cbranch_scc1 .Lk0_done
	v_exp_f32_e32 v48, v48
	v_exp_f32_e32 v49, v49
	v_exp_f32_e32 v50, v50
	v_exp_f32_e32 v51, v51
	v_exp_f32_e32 v52, v52
	v_exp_f32_e32 v53, v53
	v_exp_f32_e32 v54, v54
	v_exp_f32_e32 v55, v55
	v_cvt_pk_bf16_f32 v218, v48, v49
	v_cvt_pk_bf16_f32 v219, v50, v51
	v_cvt_pk_bf16_f32 v220, v52, v53
	v_cvt_pk_bf16_f32 v221, v54, v55
	v_exp_f32_e32 v56, v56
	v_exp_f32_e32 v57, v57
	v_mfma_f32_32x32x16_bf16 v[32:47], v[112:115], v[218:221], v[32:47]
	v_exp_f32_e32 v58, v58
	v_exp_f32_e32 v59, v59
	v_exp_f32_e32 v60, v60
	v_exp_f32_e32 v61, v61
	v_exp_f32_e32 v62, v62
	v_exp_f32_e32 v63, v63
	v_mfma_f32_32x32x16_bf16 v[16:31], v[108:111], v[218:221], v[16:31]
	v_cvt_pk_bf16_f32 v222, v56, v57
	v_cvt_pk_bf16_f32 v223, v58, v59
	v_cvt_pk_bf16_f32 v224, v60, v61
	v_cvt_pk_bf16_f32 v225, v62, v63
	v_add_f32_e32 v0, v48, v50
	v_add_f32_e32 v0, v0, v52
	v_add_f32_e32 v14, v49, v51
	v_add_f32_e32 v14, v14, v53
	v_mfma_f32_32x32x16_bf16 v[32:47], v[104:107], v[222:225], v[32:47]
	v_exp_f32_e32 v64, v64
	v_exp_f32_e32 v65, v65
	v_exp_f32_e32 v66, v66
	v_exp_f32_e32 v67, v67
	v_exp_f32_e32 v68, v68
	v_exp_f32_e32 v69, v69
	v_exp_f32_e32 v70, v70
	v_exp_f32_e32 v71, v71
	v_mfma_f32_32x32x16_bf16 v[16:31], v[100:103], v[222:225], v[16:31]
	v_cvt_pk_bf16_f32 v226, v64, v65
	v_cvt_pk_bf16_f32 v227, v66, v67
	v_cvt_pk_bf16_f32 v228, v68, v69
	v_cvt_pk_bf16_f32 v229, v70, v71
	v_add_f32_e32 v0, v0, v54
	v_add_f32_e32 v0, v0, v56
	v_add_f32_e32 v14, v14, v55
	v_add_f32_e32 v14, v14, v57
	v_mfma_f32_32x32x16_bf16 v[32:47], v[96:99], v[226:229], v[32:47]
	v_exp_f32_e32 v72, v72
	v_exp_f32_e32 v73, v73
	v_exp_f32_e32 v74, v74
	v_exp_f32_e32 v75, v75
	v_exp_f32_e32 v76, v76
	v_exp_f32_e32 v77, v77
	v_exp_f32_e32 v78, v78
	v_exp_f32_e32 v79, v79
	v_mfma_f32_32x32x16_bf16 v[16:31], v[10:13], v[226:229], v[16:31]
	s_cmp_gt_i32 s44, s41
	s_cbranch_scc1 .Lk0b_notab
	s_add_i32 s35, s48, 63
	s_min_i32 s35, s35, 192
	s_lshl_b32 s35, s35, 2
	v_subrev_u32_e32 v235, s35, v238
	s_waitcnt lgkmcnt(0)
	ds_read_b128 v[158:161], v235
	ds_read_b128 v[162:165], v235 offset:32
	ds_read_b128 v[166:169], v235 offset:64
	ds_read_b128 v[170:173], v235 offset:96
	ds_read_b128 v[174:177], v235 offset:128
	ds_read_b128 v[180:183], v235 offset:160
	ds_read_b128 v[116:119], v235 offset:192
	ds_read_b64 v[236:237], v235 offset:224
	ds_read_b32 v178, v235 offset:232
	ds_read_b32 v185, v235 offset:236
